# SwiGLU GEMM: ALIGN_EPI barrier only on a workgroup's last tile and the per-tile restart barrier dropped, so the two wave halves stay staggered across tile boundaries and one half's epilogue overlaps t
# baseline (speedup 1.0000x reference)
; #define PG8_STAGE(bufoff, gbase, voff) do { _Pragma("unroll") for (int _i = 0; _i < 2; ++_i) \
;         __builtin_amdgcn_global_load_lds((const unsigned*)((const char*)(gbase) + (voff)[_i]), (LAS unsigned*)(lds + (bufoff) + ldsw + _i * 8192), 16, 0, 0); } while (0)
; #define PG8_LDA(dst, b, h) do { _Pragma("unroll") for (int m = 0; m < 4; ++m) _Pragma("unroll") for (int k = 0; k < 2; ++k) dst[m][k] = *(const LAS h16x8*)(lds + PG8_SA(b, h) + aoff + m * 2048 + k * 1024); } while (0)
; #define PG8_LDB(dst, b, h) do { _Pragma("unroll") for (int n = 0; n < 2; ++n) _Pragma("unroll") for (int k = 0; k < 2; ++k) dst[n][k] = *(const LAS h16x8*)(lds + PG8_SB(b, h) + boff + n * 2048 + k * 1024); } while (0)
; #define PG8_MMA(ai, bj, At, Bt) do { __builtin_amdgcn_s_setprio(1); _Pragma("unroll") for (int m = 0; m < 4; ++m) _Pragma("unroll") for (int n = 0; n < 2; ++n) _Pragma("unroll") for (int k = 0; k < 2; ++k) \
;         acc[ai][bj][m][n] = __builtin_amdgcn_mfma_f32_16x16x32_f16(Bt[n][k], At[m][k], acc[ai][bj][m][n], 0, 0, 0); __builtin_amdgcn_s_setprio(0); } while (0)
; #define PG8_WAIT_V(n) asm volatile("s_waitcnt vmcnt(" #n ")" ::: "memory")
; #define PG8_WAIT_L(n) asm volatile("s_waitcnt lgkmcnt(" #n ")" ::: "memory")
; #define PG8_BAR __builtin_amdgcn_s_barrier()
; #define PG8_SCHED __builtin_amdgcn_sched_barrier(0)
; template <class Epi>
; __device__ __forceinline__ void gemm_phase(LAS unsigned char* lds, const Gemm g, const StaticOrder& S, const Epi& E) {
;     ...
;         for (int t = 0; t < nt; t += 2) {
;             const bool last = (t == nt - 2);
;             const char* a1 = cA + (size_t)(t + 1) * kstep;
;             const char* a2 = last ? nA : cA + (size_t)(t + 2) * kstep; const char* b2 = last ? nB : cB + (size_t)(t + 2) * kstep;
;             const char* a3 = a2 + kstep; const char* b3 = b2 + kstep;
;             PG8_LDB(B0, 0, 0); PG8_LDB(B1, 0, 1); PG8_SCHED; PG8_LDA(At, 0, 0); PG8_STAGE(PG8_SA(1, 1), a1 + hstepA, voffA);
;             PG8_WAIT_V(8); PG8_WAIT_L(0); PG8_BAR; PG8_MMA(0, 0, At, B0); PG8_MMA(0, 1, At, B1); PG8_BAR; PG8_SCHED;
;             PG8_LDA(At, 0, 1); PG8_STAGE(PG8_SB(0, 0), b2, voffB); PG8_STAGE(PG8_SB(0, 1), b2 + hstepB, voffB); PG8_STAGE(PG8_SA(0, 0), a2, voffA);
;             PG8_WAIT_V(8); PG8_WAIT_L(0); PG8_BAR; PG8_MMA(1, 0, At, B0); PG8_MMA(1, 1, At, B1); PG8_BAR; PG8_SCHED;
.Lprio_753:
.LBB0_753:
	s_add_u32 s20, s18, 0xfffc0080
	s_addc_u32 s21, s19, -1
	s_add_i32 s73, 0, 0x10000
	s_cmp_eq_u32 s72, 12
	s_cselect_b32 s23, s11, s21
	s_cselect_b32 s22, s68, s20
	v_add_u32_e32 v32, s73, v143
	s_cselect_b32 s21, s9, s71
	s_cselect_b32 s20, s69, s70
	s_add_i32 s75, 0, 0x14000
	ds_read_b128 v[146:149], v32
	ds_read_b128 v[150:153], v32 offset:1024
	ds_read_b128 v[154:157], v32 offset:2048
	ds_read_b128 v[158:161], v32 offset:3072
	v_add_u32_e32 v32, s75, v143
	ds_read_b128 v[162:165], v32
	ds_read_b128 v[166:169], v32 offset:1024
	ds_read_b128 v[170:173], v32 offset:2048
	ds_read_b128 v[174:177], v32 offset:3072
	v_lshl_add_u64 v[190:191], s[18:19], 0, v[140:141]
	s_add_i32 m0, s28, 0xc000
	ds_read_b128 v[178:181], v145
	ds_read_b128 v[204:207], v145 offset:1024
	ds_read_b128 v[208:211], v145 offset:2048
	ds_read_b128 v[212:215], v145 offset:3072
	ds_read_b128 v[216:219], v145 offset:4096
	ds_read_b128 v[220:223], v145 offset:5120
	ds_read_b128 v[224:227], v145 offset:6144
	ds_read_b128 v[228:231], v145 offset:7168
	global_load_lds_dwordx4 v[190:191], off
	v_lshl_add_u64 v[190:191], s[18:19], 0, v[138:139]
	s_add_i32 m0, s28, 0xe000
	s_nop 0
	global_load_lds_dwordx4 v[190:191], off
	s_waitcnt vmcnt(8)
	s_waitcnt lgkmcnt(0)
	s_barrier
	s_waitcnt lgkmcnt(0)
	v_mfma_f32_16x16x32_f16 v[126:129], v[146:149], v[178:181], v[126:129]
	v_mfma_f32_16x16x32_f16 v[118:121], v[154:157], v[178:181], v[118:121]
	v_mfma_f32_16x16x32_f16 v[110:113], v[146:149], v[208:211], v[110:113]
	v_mfma_f32_16x16x32_f16 v[102:105], v[154:157], v[208:211], v[102:105]
	v_mfma_f32_16x16x32_f16 v[94:97], v[146:149], v[216:219], v[94:97]
	v_mfma_f32_16x16x32_f16 v[86:89], v[154:157], v[216:219], v[86:89]
	v_mfma_f32_16x16x32_f16 v[78:81], v[146:149], v[224:227], v[78:81]
	v_mfma_f32_16x16x32_f16 v[70:73], v[154:157], v[224:227], v[70:73]
	v_mfma_f32_16x16x32_f16 v[126:129], v[150:153], v[204:207], v[126:129]
	v_mfma_f32_16x16x32_f16 v[118:121], v[158:161], v[204:207], v[118:121]
	v_mfma_f32_16x16x32_f16 v[110:113], v[150:153], v[212:215], v[110:113]
	v_mfma_f32_16x16x32_f16 v[102:105], v[158:161], v[212:215], v[102:105]
	v_mfma_f32_16x16x32_f16 v[94:97], v[150:153], v[220:223], v[94:97]
	v_mfma_f32_16x16x32_f16 v[86:89], v[158:161], v[220:223], v[86:89]
	v_mfma_f32_16x16x32_f16 v[78:81], v[150:153], v[228:231], v[78:81]
	v_mfma_f32_16x16x32_f16 v[70:73], v[158:161], v[228:231], v[70:73]
	v_mfma_f32_16x16x32_f16 v[122:125], v[162:165], v[178:181], v[122:125]
	v_mfma_f32_16x16x32_f16 v[114:117], v[170:173], v[178:181], v[114:117]
	v_mfma_f32_16x16x32_f16 v[106:109], v[162:165], v[208:211], v[106:109]
	v_mfma_f32_16x16x32_f16 v[98:101], v[170:173], v[208:211], v[98:101]
	v_mfma_f32_16x16x32_f16 v[90:93], v[162:165], v[216:219], v[90:93]
	v_mfma_f32_16x16x32_f16 v[82:85], v[170:173], v[216:219], v[82:85]
	v_mfma_f32_16x16x32_f16 v[74:77], v[162:165], v[224:227], v[74:77]
	v_mfma_f32_16x16x32_f16 v[66:69], v[170:173], v[224:227], v[66:69]
	v_mfma_f32_16x16x32_f16 v[122:125], v[166:169], v[204:207], v[122:125]
	v_mfma_f32_16x16x32_f16 v[114:117], v[174:177], v[204:207], v[114:117]
	v_mfma_f32_16x16x32_f16 v[106:109], v[166:169], v[212:215], v[106:109]
	v_mfma_f32_16x16x32_f16 v[98:101], v[174:177], v[212:215], v[98:101]
	v_mfma_f32_16x16x32_f16 v[90:93], v[166:169], v[220:223], v[90:93]
	v_mfma_f32_16x16x32_f16 v[82:85], v[174:177], v[220:223], v[82:85]
	v_mfma_f32_16x16x32_f16 v[74:77], v[166:169], v[228:231], v[74:77]
	v_mfma_f32_16x16x32_f16 v[66:69], v[174:177], v[228:231], v[66:69]
	s_barrier
	s_add_i32 s73, s73, s3
	v_lshl_add_u64 v[190:191], s[20:21], 0, v[134:135]
	s_mov_b32 m0, s73
	ds_read_b128 v[178:181], v145 offset:16384
	ds_read_b128 v[204:207], v145 offset:17408
	ds_read_b128 v[208:211], v145 offset:18432
	ds_read_b128 v[212:215], v145 offset:19456
	ds_read_b128 v[216:219], v145 offset:20480
	ds_read_b128 v[220:223], v145 offset:21504
	ds_read_b128 v[224:227], v145 offset:22528
	ds_read_b128 v[228:231], v145 offset:23552
	global_load_lds_dwordx4 v[190:191], off
	s_add_i32 m0, s73, 0x2000
	s_add_u32 s76, s20, 0x40000
	v_lshl_add_u64 v[196:197], s[20:21], 0, v[130:131]
	s_addc_u32 s77, s21, 0
	s_add_i32 s73, s75, s3
	global_load_lds_dwordx4 v[196:197], off
	v_lshl_add_u64 v[198:199], s[76:77], 0, v[134:135]
	s_mov_b32 m0, s73
	v_lshl_add_u64 v[232:233], s[22:23], 0, v[132:133]
	global_load_lds_dwordx4 v[198:199], off
	v_lshl_add_u64 v[198:199], s[76:77], 0, v[130:131]
	s_add_i32 m0, s73, 0x2000
	s_nop 0
	global_load_lds_dwordx4 v[198:199], off
	v_lshl_add_u64 v[198:199], s[22:23], 0, v[136:137]
	s_mov_b32 m0, s28
	s_nop 0
	global_load_lds_dwordx4 v[198:199], off
	s_mov_b32 m0, s29
	s_nop 0
	global_load_lds_dwordx4 v[232:233], off
	s_waitcnt vmcnt(8)
	s_waitcnt lgkmcnt(0)
	s_barrier
; #define PG8_STAGE(bufoff, gbase, voff) do { _Pragma("unroll") for (int _i = 0; _i < 2; ++_i) \
;         __builtin_amdgcn_global_load_lds((const unsigned*)((const char*)(gbase) + (voff)[_i]), (LAS unsigned*)(lds + (bufoff) + ldsw + _i * 8192), 16, 0, 0); } while (0)
; #define PG8_LDA(dst, b, h) do { _Pragma("unroll") for (int m = 0; m < 4; ++m) _Pragma("unroll") for (int k = 0; k < 2; ++k) dst[m][k] = *(const LAS h16x8*)(lds + PG8_SA(b, h) + aoff + m * 2048 + k * 1024); } while (0)
; #define PG8_LDB(dst, b, h) do { _Pragma("unroll") for (int n = 0; n < 2; ++n) _Pragma("unroll") for (int k = 0; k < 2; ++k) dst[n][k] = *(const LAS h16x8*)(lds + PG8_SB(b, h) + boff + n * 2048 + k * 1024); } while (0)
; #define PG8_MMA(ai, bj, At, Bt) do { __builtin_amdgcn_s_setprio(1); _Pragma("unroll") for (int m = 0; m < 4; ++m) _Pragma("unroll") for (int n = 0; n < 2; ++n) _Pragma("unroll") for (int k = 0; k < 2; ++k) \
;         acc[ai][bj][m][n] = __builtin_amdgcn_mfma_f32_16x16x32_f16(Bt[n][k], At[m][k], acc[ai][bj][m][n], 0, 0, 0); __builtin_amdgcn_s_setprio(0); } while (0)
; #define PG8_WAIT_V(n) asm volatile("s_waitcnt vmcnt(" #n ")" ::: "memory")
; #define PG8_WAIT_L(n) asm volatile("s_waitcnt lgkmcnt(" #n ")" ::: "memory")
; #define PG8_BAR __builtin_amdgcn_s_barrier()
; #define PG8_SCHED __builtin_amdgcn_sched_barrier(0)
; template <class Epi>
; __device__ __forceinline__ void gemm_phase(LAS unsigned char* lds, const Gemm g, const StaticOrder& S, const Epi& E) {
;     ...
;             PG8_WAIT_V(8); PG8_WAIT_L(0); PG8_BAR; PG8_MMA(1, 0, At, B0); PG8_MMA(1, 1, At, B1); PG8_BAR; PG8_SCHED;
;             PG8_LDB(B0, 1, 0); PG8_LDB(B1, 1, 1); PG8_SCHED; PG8_LDA(At, 1, 0); PG8_STAGE(PG8_SA(0, 1), a2 + hstepA, voffA);
;             PG8_WAIT_V(8); PG8_WAIT_L(0); PG8_BAR; PG8_MMA(0, 0, At, B0); PG8_MMA(0, 1, At, B1); PG8_BAR; PG8_SCHED;
	s_waitcnt lgkmcnt(0)
	v_mfma_f32_16x16x32_f16 v[62:65], v[146:149], v[178:181], v[62:65]
	v_mfma_f32_16x16x32_f16 v[54:57], v[154:157], v[178:181], v[54:57]
	v_mfma_f32_16x16x32_f16 v[46:49], v[146:149], v[208:211], v[46:49]
	v_mfma_f32_16x16x32_f16 v[38:41], v[154:157], v[208:211], v[38:41]
	v_mfma_f32_16x16x32_f16 v[28:31], v[146:149], v[216:219], v[28:31]
	v_mfma_f32_16x16x32_f16 v[20:23], v[154:157], v[216:219], v[20:23]
	v_mfma_f32_16x16x32_f16 v[12:15], v[146:149], v[224:227], v[12:15]
	v_mfma_f32_16x16x32_f16 v[4:7], v[154:157], v[224:227], v[4:7]
	v_mfma_f32_16x16x32_f16 v[62:65], v[150:153], v[204:207], v[62:65]
	v_mfma_f32_16x16x32_f16 v[54:57], v[158:161], v[204:207], v[54:57]
	v_mfma_f32_16x16x32_f16 v[46:49], v[150:153], v[212:215], v[46:49]
	v_mfma_f32_16x16x32_f16 v[38:41], v[158:161], v[212:215], v[38:41]
	v_mfma_f32_16x16x32_f16 v[28:31], v[150:153], v[220:223], v[28:31]
	v_mfma_f32_16x16x32_f16 v[20:23], v[158:161], v[220:223], v[20:23]
	v_mfma_f32_16x16x32_f16 v[12:15], v[150:153], v[228:231], v[12:15]
	v_mfma_f32_16x16x32_f16 v[4:7], v[158:161], v[228:231], v[4:7]
	v_mfma_f32_16x16x32_f16 v[58:61], v[162:165], v[178:181], v[58:61]
	v_mfma_f32_16x16x32_f16 v[50:53], v[170:173], v[178:181], v[50:53]
	v_mfma_f32_16x16x32_f16 v[42:45], v[162:165], v[208:211], v[42:45]
	v_mfma_f32_16x16x32_f16 v[34:37], v[170:173], v[208:211], v[34:37]
	v_mfma_f32_16x16x32_f16 v[24:27], v[162:165], v[216:219], v[24:27]
	v_mfma_f32_16x16x32_f16 v[16:19], v[170:173], v[216:219], v[16:19]
	v_mfma_f32_16x16x32_f16 v[8:11], v[162:165], v[224:227], v[8:11]
	v_mfma_f32_16x16x32_f16 v[0:3], v[170:173], v[224:227], v[0:3]
	v_mfma_f32_16x16x32_f16 v[58:61], v[166:169], v[204:207], v[58:61]
	v_mfma_f32_16x16x32_f16 v[50:53], v[174:177], v[204:207], v[50:53]
	v_mfma_f32_16x16x32_f16 v[42:45], v[166:169], v[212:215], v[42:45]
	v_mfma_f32_16x16x32_f16 v[34:37], v[174:177], v[212:215], v[34:37]
	v_mfma_f32_16x16x32_f16 v[24:27], v[166:169], v[220:223], v[24:27]
	v_mfma_f32_16x16x32_f16 v[16:19], v[174:177], v[220:223], v[16:19]
	v_mfma_f32_16x16x32_f16 v[8:11], v[166:169], v[228:231], v[8:11]
	v_mfma_f32_16x16x32_f16 v[0:3], v[174:177], v[228:231], v[0:3]
	s_barrier
	s_add_i32 s73, 0, 0x18000
	v_add_u32_e32 v32, s73, v143
	s_add_i32 s75, 0, 0x1c000
	ds_read_b128 v[146:149], v32
	ds_read_b128 v[150:153], v32 offset:1024
	ds_read_b128 v[154:157], v32 offset:2048
	ds_read_b128 v[158:161], v32 offset:3072
	v_add_u32_e32 v32, s75, v143
	ds_read_b128 v[162:165], v32
	ds_read_b128 v[166:169], v32 offset:1024
	ds_read_b128 v[170:173], v32 offset:2048
	ds_read_b128 v[174:177], v32 offset:3072
	s_add_u32 s22, s22, 0x40000
	s_addc_u32 s23, s23, 0
	s_mov_b32 m0, s30
	v_lshl_add_u64 v[234:235], s[22:23], 0, v[136:137]
	ds_read_b128 v[178:181], v145 offset:32768
	ds_read_b128 v[204:207], v145 offset:33792
	ds_read_b128 v[208:211], v145 offset:34816
	ds_read_b128 v[212:215], v145 offset:35840
	ds_read_b128 v[216:219], v145 offset:36864
	ds_read_b128 v[220:223], v145 offset:37888
	ds_read_b128 v[224:227], v145 offset:38912
	ds_read_b128 v[228:231], v145 offset:39936
	global_load_lds_dwordx4 v[234:235], off
	v_lshl_add_u64 v[234:235], s[22:23], 0, v[132:133]
	s_mov_b32 m0, s31
	s_nop 0
	global_load_lds_dwordx4 v[234:235], off
	s_waitcnt vmcnt(8)
	s_waitcnt lgkmcnt(0)
	s_barrier
	s_waitcnt lgkmcnt(0)
	v_mfma_f32_16x16x32_f16 v[126:129], v[146:149], v[178:181], v[126:129]
	v_mfma_f32_16x16x32_f16 v[118:121], v[154:157], v[178:181], v[118:121]
	v_mfma_f32_16x16x32_f16 v[110:113], v[146:149], v[208:211], v[110:113]
	v_mfma_f32_16x16x32_f16 v[102:105], v[154:157], v[208:211], v[102:105]
	v_mfma_f32_16x16x32_f16 v[94:97], v[146:149], v[216:219], v[94:97]
	v_mfma_f32_16x16x32_f16 v[86:89], v[154:157], v[216:219], v[86:89]
	v_mfma_f32_16x16x32_f16 v[78:81], v[146:149], v[224:227], v[78:81]
	v_mfma_f32_16x16x32_f16 v[70:73], v[154:157], v[224:227], v[70:73]
	v_mfma_f32_16x16x32_f16 v[126:129], v[150:153], v[204:207], v[126:129]
	v_mfma_f32_16x16x32_f16 v[118:121], v[158:161], v[204:207], v[118:121]
	v_mfma_f32_16x16x32_f16 v[110:113], v[150:153], v[212:215], v[110:113]
	v_mfma_f32_16x16x32_f16 v[102:105], v[158:161], v[212:215], v[102:105]
	v_mfma_f32_16x16x32_f16 v[94:97], v[150:153], v[220:223], v[94:97]
	v_mfma_f32_16x16x32_f16 v[86:89], v[158:161], v[220:223], v[86:89]
	v_mfma_f32_16x16x32_f16 v[78:81], v[150:153], v[228:231], v[78:81]
	v_mfma_f32_16x16x32_f16 v[70:73], v[158:161], v[228:231], v[70:73]
	v_mfma_f32_16x16x32_f16 v[122:125], v[162:165], v[178:181], v[122:125]
	v_mfma_f32_16x16x32_f16 v[114:117], v[170:173], v[178:181], v[114:117]
	v_mfma_f32_16x16x32_f16 v[106:109], v[162:165], v[208:211], v[106:109]
	v_mfma_f32_16x16x32_f16 v[98:101], v[170:173], v[208:211], v[98:101]
	v_mfma_f32_16x16x32_f16 v[90:93], v[162:165], v[216:219], v[90:93]
	v_mfma_f32_16x16x32_f16 v[82:85], v[170:173], v[216:219], v[82:85]
	v_mfma_f32_16x16x32_f16 v[74:77], v[162:165], v[224:227], v[74:77]
	v_mfma_f32_16x16x32_f16 v[66:69], v[170:173], v[224:227], v[66:69]
	v_mfma_f32_16x16x32_f16 v[122:125], v[166:169], v[204:207], v[122:125]
	v_mfma_f32_16x16x32_f16 v[114:117], v[174:177], v[204:207], v[114:117]
	v_mfma_f32_16x16x32_f16 v[106:109], v[166:169], v[212:215], v[106:109]
	v_mfma_f32_16x16x32_f16 v[98:101], v[174:177], v[212:215], v[98:101]
	v_mfma_f32_16x16x32_f16 v[90:93], v[166:169], v[220:223], v[90:93]
	v_mfma_f32_16x16x32_f16 v[82:85], v[174:177], v[220:223], v[82:85]
	v_mfma_f32_16x16x32_f16 v[74:77], v[166:169], v[228:231], v[74:77]
	v_mfma_f32_16x16x32_f16 v[66:69], v[174:177], v[228:231], v[66:69]
	s_barrier
; __device__ __forceinline__ float silu_f(float x) { return x * __builtin_amdgcn_rcpf(1.0f + fexp(-x)); }
; #define PG8_STAGE(bufoff, gbase, voff) do { _Pragma("unroll") for (int _i = 0; _i < 2; ++_i) \
;         __builtin_amdgcn_global_load_lds((const unsigned*)((const char*)(gbase) + (voff)[_i]), (LAS unsigned*)(lds + (bufoff) + ldsw + _i * 8192), 16, 0, 0); } while (0)
; #define PG8_LDA(dst, b, h) do { _Pragma("unroll") for (int m = 0; m < 4; ++m) _Pragma("unroll") for (int k = 0; k < 2; ++k) dst[m][k] = *(const LAS h16x8*)(lds + PG8_SA(b, h) + aoff + m * 2048 + k * 1024); } while (0)
; #define PG8_MMA(ai, bj, At, Bt) do { __builtin_amdgcn_s_setprio(1); _Pragma("unroll") for (int m = 0; m < 4; ++m) _Pragma("unroll") for (int n = 0; n < 2; ++n) _Pragma("unroll") for (int k = 0; k < 2; ++k) \
;         acc[ai][bj][m][n] = __builtin_amdgcn_mfma_f32_16x16x32_f16(Bt[n][k], At[m][k], acc[ai][bj][m][n], 0, 0, 0); __builtin_amdgcn_s_setprio(0); } while (0)
; #define PG8_WAIT_V(n) asm volatile("s_waitcnt vmcnt(" #n ")" ::: "memory")
; #define PG8_BAR __builtin_amdgcn_s_barrier()
;     __device__ __forceinline__ void operator()(const f32x4 (&acc)[2][2][4][2], const Unit& u, int wr, int wc, int fr, int fq) const {
;         const int row0 = u.pm * BM + wr * 64 + fr, col0 = u.pn * 128 + wc * 32 + 8 * fq;
; #pragma unroll
;         for (int ai = 0; ai < 2; ++ai)
; #pragma unroll
;             for (int m = 0; m < 4; ++m) {
;                 h16x8 o;
; #pragma unroll
;                 for (int n = 0; n < 2; ++n)
; #pragma unroll
;                     for (int j = 0; j < 4; ++j) o[4 * n + j] = (h16)(silu_f(acc[ai][0][m][n][j]) * acc[ai][1][m][n][j]);
;                 *(h16x8*)(O + (unsigned)(row0 + ai * HALF + m * 16) * FF + col0) = o;
; template <class Epi>
; __device__ __forceinline__ void gemm_phase(LAS unsigned char* lds, const Gemm g, const StaticOrder& S, const Epi& E) {
;     ...
;             PG8_WAIT_V(8); PG8_WAIT_L(0); PG8_BAR; PG8_MMA(0, 0, At, B0); PG8_MMA(0, 1, At, B1); PG8_BAR; PG8_SCHED;
;             PG8_LDA(At, 1, 1); PG8_STAGE(PG8_SB(1, 0), b3, voffB); PG8_STAGE(PG8_SB(1, 1), b3 + hstepB, voffB); PG8_STAGE(PG8_SA(1, 0), a3, voffA);
;             PG8_WAIT_V(8); PG8_WAIT_L(0); PG8_BAR; PG8_MMA(1, 0, At, B0); PG8_MMA(1, 1, At, B1); PG8_BAR; PG8_SCHED;
;         }
;         if (wr == 0) PG8_BAR;
;         E(acc, cur, wr, wc, fr, fq);
	s_add_i32 s22, s73, s3
	v_lshl_add_u64 v[190:191], v[190:191], 0, s[90:91]
	s_mov_b32 m0, s22
	ds_read_b128 v[178:181], v145 offset:49152
	ds_read_b128 v[204:207], v145 offset:50176
	ds_read_b128 v[208:211], v145 offset:51200
	ds_read_b128 v[212:215], v145 offset:52224
	ds_read_b128 v[216:219], v145 offset:53248
	ds_read_b128 v[220:223], v145 offset:54272
	ds_read_b128 v[224:227], v145 offset:55296
	ds_read_b128 v[228:231], v145 offset:56320
	global_load_lds_dwordx4 v[190:191], off
	s_add_i32 m0, s22, 0x2000
	s_add_u32 s20, s20, 0x40080
	v_lshl_add_u64 v[190:191], v[196:197], 0, s[90:91]
	s_addc_u32 s21, s21, 0
	s_add_i32 s22, s75, s3
	global_load_lds_dwordx4 v[190:191], off
	v_lshl_add_u64 v[190:191], s[20:21], 0, v[134:135]
	s_mov_b32 m0, s22
	s_nop 0
	global_load_lds_dwordx4 v[190:191], off
	v_lshl_add_u64 v[190:191], s[20:21], 0, v[130:131]
	s_add_i32 m0, s22, 0x2000
	s_nop 0
	global_load_lds_dwordx4 v[190:191], off
	v_lshl_add_u64 v[190:191], v[198:199], 0, s[90:91]
	s_mov_b32 m0, s35
	s_nop 0
	global_load_lds_dwordx4 v[190:191], off
	v_lshl_add_u64 v[190:191], v[232:233], 0, s[90:91]
	s_mov_b32 m0, s54
	s_nop 0
	global_load_lds_dwordx4 v[190:191], off
	s_waitcnt vmcnt(8)
	s_waitcnt lgkmcnt(0)
	s_barrier
	s_waitcnt lgkmcnt(0)
	v_mfma_f32_16x16x32_f16 v[62:65], v[146:149], v[178:181], v[62:65]
	v_mfma_f32_16x16x32_f16 v[54:57], v[154:157], v[178:181], v[54:57]
	v_mfma_f32_16x16x32_f16 v[46:49], v[146:149], v[208:211], v[46:49]
	v_mfma_f32_16x16x32_f16 v[38:41], v[154:157], v[208:211], v[38:41]
	v_mfma_f32_16x16x32_f16 v[28:31], v[146:149], v[216:219], v[28:31]
	v_mfma_f32_16x16x32_f16 v[20:23], v[154:157], v[216:219], v[20:23]
	v_mfma_f32_16x16x32_f16 v[12:15], v[146:149], v[224:227], v[12:15]
	v_mfma_f32_16x16x32_f16 v[4:7], v[154:157], v[224:227], v[4:7]
	v_mfma_f32_16x16x32_f16 v[62:65], v[150:153], v[204:207], v[62:65]
	v_mfma_f32_16x16x32_f16 v[54:57], v[158:161], v[204:207], v[54:57]
	v_mfma_f32_16x16x32_f16 v[46:49], v[150:153], v[212:215], v[46:49]
	v_mfma_f32_16x16x32_f16 v[38:41], v[158:161], v[212:215], v[38:41]
	v_mfma_f32_16x16x32_f16 v[28:31], v[150:153], v[220:223], v[28:31]
	v_mfma_f32_16x16x32_f16 v[20:23], v[158:161], v[220:223], v[20:23]
	v_mfma_f32_16x16x32_f16 v[12:15], v[150:153], v[228:231], v[12:15]
	v_mfma_f32_16x16x32_f16 v[4:7], v[158:161], v[228:231], v[4:7]
	v_mfma_f32_16x16x32_f16 v[58:61], v[162:165], v[178:181], v[58:61]
	v_mfma_f32_16x16x32_f16 v[50:53], v[170:173], v[178:181], v[50:53]
	v_mfma_f32_16x16x32_f16 v[42:45], v[162:165], v[208:211], v[42:45]
	v_mfma_f32_16x16x32_f16 v[34:37], v[170:173], v[208:211], v[34:37]
	v_mfma_f32_16x16x32_f16 v[24:27], v[162:165], v[216:219], v[24:27]
	v_mfma_f32_16x16x32_f16 v[16:19], v[170:173], v[216:219], v[16:19]
	v_mfma_f32_16x16x32_f16 v[8:11], v[162:165], v[224:227], v[8:11]
	v_mfma_f32_16x16x32_f16 v[0:3], v[170:173], v[224:227], v[0:3]
	v_mfma_f32_16x16x32_f16 v[58:61], v[166:169], v[204:207], v[58:61]
	v_mfma_f32_16x16x32_f16 v[50:53], v[174:177], v[204:207], v[50:53]
	v_mfma_f32_16x16x32_f16 v[42:45], v[166:169], v[212:215], v[42:45]
	v_mfma_f32_16x16x32_f16 v[34:37], v[174:177], v[212:215], v[34:37]
	v_mfma_f32_16x16x32_f16 v[24:27], v[166:169], v[220:223], v[24:27]
	v_mfma_f32_16x16x32_f16 v[16:19], v[174:177], v[220:223], v[16:19]
	v_mfma_f32_16x16x32_f16 v[8:11], v[166:169], v[228:231], v[8:11]
	v_mfma_f32_16x16x32_f16 v[0:3], v[174:177], v[228:231], v[0:3]
	s_barrier
	s_add_i32 s72, s72, 2
	s_add_u32 s70, s70, 0x100
	s_addc_u32 s71, s71, 0
	s_add_u32 s18, s18, 0x100
	s_addc_u32 s19, s19, 0
	s_cmp_gt_u32 s72, 13
	s_cbranch_scc0 .LBB0_753
	s_setprio 0
	s_and_b64 vcc, exec, s[6:7]
	s_cbranch_vccz .LBB0_756
	s_and_b64 vcc, exec, s[4:5]
	s_cbranch_vccnz .LBB0_756
	s_barrier
.LBB0_756:
	s_mov_b32 s18, 0xbfb8aa3b
	s_mov_b32 s19, 0xbfb8aa3b
	v_lshl_add_u32 v32, s16, 8, v142
	v_lshl_or_b32 v146, s17, 7, v144
	s_movk_i32 s9, 0xb00
	v_ashrrev_i32_e32 v147, 31, v146
	v_mul_lo_u32 v32, v32, s9
	s_mov_b64 s[16:17], -1
	s_andn2_b64 vcc, exec, s[4:5]
	v_lshl_add_u64 v[230:231], v[32:33], 1, s[86:87]
	v_lshlrev_b64 v[232:233], 1, v[146:147]
	v_lshl_add_u64 v[230:231], v[230:231], 0, v[232:233]
	v_pk_mul_f32 v[150:151], v[126:127], s[18:19]
	v_pk_mul_f32 v[152:153], v[128:129], s[18:19]
	v_pk_mul_f32 v[154:155], v[118:119], s[18:19]
	v_pk_mul_f32 v[156:157], v[120:121], s[18:19]
	v_exp_f32_e32 v150, v150
	v_exp_f32_e32 v152, v152
	v_exp_f32_e32 v154, v154
	v_exp_f32_e32 v156, v156
	v_exp_f32_e32 v151, v151
	v_exp_f32_e32 v153, v153
	v_exp_f32_e32 v155, v155
	v_exp_f32_e32 v157, v157
	v_pk_add_f32 v[150:151], v[150:151], 1.0 op_sel_hi:[1,0]
	v_pk_add_f32 v[152:153], v[152:153], 1.0 op_sel_hi:[1,0]
	v_pk_add_f32 v[154:155], v[154:155], 1.0 op_sel_hi:[1,0]
	v_pk_add_f32 v[156:157], v[156:157], 1.0 op_sel_hi:[1,0]
	v_rcp_f32_e32 v150, v150
	v_rcp_f32_e32 v152, v152
	v_rcp_f32_e32 v154, v154
	v_rcp_f32_e32 v156, v156
	v_rcp_f32_e32 v151, v151
	v_rcp_f32_e32 v153, v153
	v_rcp_f32_e32 v155, v155
	v_rcp_f32_e32 v157, v157
	v_pk_mul_f32 v[150:151], v[126:127], v[150:151]
	v_pk_mul_f32 v[152:153], v[128:129], v[152:153]
	v_pk_mul_f32 v[154:155], v[118:119], v[154:155]
	v_pk_mul_f32 v[156:157], v[120:121], v[156:157]
	v_pk_mul_f32 v[150:151], v[150:151], v[122:123]
	v_pk_mul_f32 v[152:153], v[152:153], v[124:125]
	v_pk_mul_f32 v[154:155], v[154:155], v[114:115]
	v_pk_mul_f32 v[156:157], v[156:157], v[116:117]
	v_cvt_pk_f16_f32 v122, v150, v151
	v_cvt_pk_f16_f32 v123, v152, v153
	v_cvt_pk_f16_f32 v124, v154, v155
	v_cvt_pk_f16_f32 v125, v156, v157
	s_nop 0
	global_store_dwordx4 v[230:231], v[122:125], off
	v_add_u32_e32 v234, 0xb000, v32
	v_mov_b32_e32 v235, v33
; __device__ __forceinline__ float silu_f(float x) { return x * __builtin_amdgcn_rcpf(1.0f + fexp(-x)); }
;     __device__ __forceinline__ void operator()(const f32x4 (&acc)[2][2][4][2], const Unit& u, int wr, int wc, int fr, int fq) const {
;         const int row0 = u.pm * BM + wr * 64 + fr, col0 = u.pn * 128 + wc * 32 + 8 * fq;
; #pragma unroll
;         for (int ai = 0; ai < 2; ++ai)
; #pragma unroll
;             for (int m = 0; m < 4; ++m) {
;                 h16x8 o;
; #pragma unroll
;                 for (int n = 0; n < 2; ++n)
; #pragma unroll
;                     for (int j = 0; j < 4; ++j) o[4 * n + j] = (h16)(silu_f(acc[ai][0][m][n][j]) * acc[ai][1][m][n][j]);
;                 *(h16x8*)(O + (unsigned)(row0 + ai * HALF + m * 16) * FF + col0) = o;
	v_lshl_add_u64 v[234:235], v[234:235], 1, s[86:87]
	v_lshl_add_u64 v[234:235], v[234:235], 0, v[232:233]
	v_pk_mul_f32 v[158:159], v[110:111], s[18:19]
	v_pk_mul_f32 v[160:161], v[112:113], s[18:19]
	v_pk_mul_f32 v[162:163], v[102:103], s[18:19]
	v_pk_mul_f32 v[164:165], v[104:105], s[18:19]
	v_exp_f32_e32 v158, v158
	v_exp_f32_e32 v160, v160
	v_exp_f32_e32 v162, v162
	v_exp_f32_e32 v164, v164
	v_exp_f32_e32 v159, v159
	v_exp_f32_e32 v161, v161
	v_exp_f32_e32 v163, v163
	v_exp_f32_e32 v165, v165
	v_pk_add_f32 v[158:159], v[158:159], 1.0 op_sel_hi:[1,0]
	v_pk_add_f32 v[160:161], v[160:161], 1.0 op_sel_hi:[1,0]
	v_pk_add_f32 v[162:163], v[162:163], 1.0 op_sel_hi:[1,0]
	v_pk_add_f32 v[164:165], v[164:165], 1.0 op_sel_hi:[1,0]
	v_rcp_f32_e32 v158, v158
	v_rcp_f32_e32 v160, v160
	v_rcp_f32_e32 v162, v162
	v_rcp_f32_e32 v164, v164
	v_rcp_f32_e32 v159, v159
	v_rcp_f32_e32 v161, v161
	v_rcp_f32_e32 v163, v163
	v_rcp_f32_e32 v165, v165
	v_pk_mul_f32 v[158:159], v[110:111], v[158:159]
	v_pk_mul_f32 v[160:161], v[112:113], v[160:161]
	v_pk_mul_f32 v[162:163], v[102:103], v[162:163]
	v_pk_mul_f32 v[164:165], v[104:105], v[164:165]
	v_pk_mul_f32 v[158:159], v[158:159], v[106:107]
	v_pk_mul_f32 v[160:161], v[160:161], v[108:109]
	v_pk_mul_f32 v[162:163], v[162:163], v[98:99]
	v_pk_mul_f32 v[164:165], v[164:165], v[100:101]
	v_cvt_pk_f16_f32 v106, v158, v159
	v_cvt_pk_f16_f32 v107, v160, v161
	v_cvt_pk_f16_f32 v108, v162, v163
	v_cvt_pk_f16_f32 v109, v164, v165
	s_nop 0
	global_store_dwordx4 v[234:235], v[106:109], off
	v_add_u32_e32 v236, 0x16000, v32
	v_mov_b32_e32 v237, v33
	v_lshl_add_u64 v[236:237], v[236:237], 1, s[86:87]
	v_lshl_add_u64 v[236:237], v[236:237], 0, v[232:233]
	v_pk_mul_f32 v[150:151], v[94:95], s[18:19]
	v_pk_mul_f32 v[152:153], v[96:97], s[18:19]
	v_pk_mul_f32 v[154:155], v[86:87], s[18:19]
	v_pk_mul_f32 v[156:157], v[88:89], s[18:19]
	v_exp_f32_e32 v150, v150
	v_exp_f32_e32 v152, v152
	v_exp_f32_e32 v154, v154
	v_exp_f32_e32 v156, v156
	v_exp_f32_e32 v151, v151
	v_exp_f32_e32 v153, v153
	v_exp_f32_e32 v155, v155
	v_exp_f32_e32 v157, v157
	v_pk_add_f32 v[150:151], v[150:151], 1.0 op_sel_hi:[1,0]
	v_pk_add_f32 v[152:153], v[152:153], 1.0 op_sel_hi:[1,0]
	v_pk_add_f32 v[154:155], v[154:155], 1.0 op_sel_hi:[1,0]
	v_pk_add_f32 v[156:157], v[156:157], 1.0 op_sel_hi:[1,0]
	v_rcp_f32_e32 v150, v150
	v_rcp_f32_e32 v152, v152
	v_rcp_f32_e32 v154, v154
	v_rcp_f32_e32 v156, v156
	v_rcp_f32_e32 v151, v151
	v_rcp_f32_e32 v153, v153
	v_rcp_f32_e32 v155, v155
	v_rcp_f32_e32 v157, v157
	v_pk_mul_f32 v[150:151], v[94:95], v[150:151]
	v_pk_mul_f32 v[152:153], v[96:97], v[152:153]
	v_pk_mul_f32 v[154:155], v[86:87], v[154:155]
	v_pk_mul_f32 v[156:157], v[88:89], v[156:157]
	v_pk_mul_f32 v[150:151], v[150:151], v[90:91]
	v_pk_mul_f32 v[152:153], v[152:153], v[92:93]
	v_pk_mul_f32 v[154:155], v[154:155], v[82:83]
	v_pk_mul_f32 v[156:157], v[156:157], v[84:85]
	v_cvt_pk_f16_f32 v90, v150, v151
	v_cvt_pk_f16_f32 v91, v152, v153
	v_cvt_pk_f16_f32 v92, v154, v155
	v_cvt_pk_f16_f32 v93, v156, v157
	s_nop 0
	global_store_dwordx4 v[236:237], v[90:93], off
	v_add_u32_e32 v238, 0x21000, v32
	v_mov_b32_e32 v239, v33
	v_lshl_add_u64 v[238:239], v[238:239], 1, s[86:87]
	v_lshl_add_u64 v[238:239], v[238:239], 0, v[232:233]
	v_pk_mul_f32 v[158:159], v[78:79], s[18:19]
	v_pk_mul_f32 v[160:161], v[80:81], s[18:19]
	v_pk_mul_f32 v[162:163], v[70:71], s[18:19]
	v_pk_mul_f32 v[164:165], v[72:73], s[18:19]
	v_exp_f32_e32 v158, v158
	v_exp_f32_e32 v160, v160
	v_exp_f32_e32 v162, v162
	v_exp_f32_e32 v164, v164
	v_exp_f32_e32 v159, v159
	v_exp_f32_e32 v161, v161
	v_exp_f32_e32 v163, v163
	v_exp_f32_e32 v165, v165
	v_pk_add_f32 v[158:159], v[158:159], 1.0 op_sel_hi:[1,0]
	v_pk_add_f32 v[160:161], v[160:161], 1.0 op_sel_hi:[1,0]
	v_pk_add_f32 v[162:163], v[162:163], 1.0 op_sel_hi:[1,0]
	v_pk_add_f32 v[164:165], v[164:165], 1.0 op_sel_hi:[1,0]
	v_rcp_f32_e32 v158, v158
	v_rcp_f32_e32 v160, v160
	v_rcp_f32_e32 v162, v162
	v_rcp_f32_e32 v164, v164
	v_rcp_f32_e32 v159, v159
	v_rcp_f32_e32 v161, v161
	v_rcp_f32_e32 v163, v163
	v_rcp_f32_e32 v165, v165
	v_pk_mul_f32 v[158:159], v[78:79], v[158:159]
	v_pk_mul_f32 v[160:161], v[80:81], v[160:161]
	v_pk_mul_f32 v[162:163], v[70:71], v[162:163]
	v_pk_mul_f32 v[164:165], v[72:73], v[164:165]
	v_pk_mul_f32 v[158:159], v[158:159], v[74:75]
	v_pk_mul_f32 v[160:161], v[160:161], v[76:77]
	v_pk_mul_f32 v[162:163], v[162:163], v[66:67]
	v_pk_mul_f32 v[164:165], v[164:165], v[68:69]
	v_cvt_pk_f16_f32 v74, v158, v159
	v_cvt_pk_f16_f32 v75, v160, v161
	v_cvt_pk_f16_f32 v76, v162, v163
	v_cvt_pk_f16_f32 v77, v164, v165
	s_nop 0
	global_store_dwordx4 v[238:239], v[74:77], off
	v_add_u32_e32 v240, 0x58000, v32
	v_mov_b32_e32 v241, v33
	v_lshl_add_u64 v[240:241], v[240:241], 1, s[86:87]
	v_lshl_add_u64 v[240:241], v[240:241], 0, v[232:233]
	v_pk_mul_f32 v[150:151], v[62:63], s[18:19]
	v_pk_mul_f32 v[152:153], v[64:65], s[18:19]
	v_pk_mul_f32 v[154:155], v[54:55], s[18:19]
	v_pk_mul_f32 v[156:157], v[56:57], s[18:19]
	v_exp_f32_e32 v150, v150
	v_exp_f32_e32 v152, v152
	v_exp_f32_e32 v154, v154
	v_exp_f32_e32 v156, v156
	v_exp_f32_e32 v151, v151
	v_exp_f32_e32 v153, v153
	v_exp_f32_e32 v155, v155
	v_exp_f32_e32 v157, v157
	v_pk_add_f32 v[150:151], v[150:151], 1.0 op_sel_hi:[1,0]
	v_pk_add_f32 v[152:153], v[152:153], 1.0 op_sel_hi:[1,0]
	v_pk_add_f32 v[154:155], v[154:155], 1.0 op_sel_hi:[1,0]
	v_pk_add_f32 v[156:157], v[156:157], 1.0 op_sel_hi:[1,0]
	v_rcp_f32_e32 v150, v150
	v_rcp_f32_e32 v152, v152
; __device__ __forceinline__ float silu_f(float x) { return x * __builtin_amdgcn_rcpf(1.0f + fexp(-x)); }
; #define PG8_BAR __builtin_amdgcn_s_barrier()
;     __device__ __forceinline__ void operator()(const f32x4 (&acc)[2][2][4][2], const Unit& u, int wr, int wc, int fr, int fq) const {
;         const int row0 = u.pm * BM + wr * 64 + fr, col0 = u.pn * 128 + wc * 32 + 8 * fq;
; #pragma unroll
;         for (int ai = 0; ai < 2; ++ai)
; #pragma unroll
;             for (int m = 0; m < 4; ++m) {
;                 h16x8 o;
; #pragma unroll
;                 for (int n = 0; n < 2; ++n)
; #pragma unroll
;                     for (int j = 0; j < 4; ++j) o[4 * n + j] = (h16)(silu_f(acc[ai][0][m][n][j]) * acc[ai][1][m][n][j]);
;                 *(h16x8*)(O + (unsigned)(row0 + ai * HALF + m * 16) * FF + col0) = o;
; template <class Epi>
; __device__ __forceinline__ void gemm_phase(LAS unsigned char* lds, const Gemm g, const StaticOrder& S, const Epi& E) {
;     ...
;         if (!has_next) break;
; #pragma unroll
;         for (int a = 0; a < 2; ++a)
; #pragma unroll
;             for (int b = 0; b < 2; ++b)
; #pragma unroll
;                 for (int m = 0; m < 4; ++m)
; #pragma unroll
;                     for (int n = 0; n < 2; ++n) acc[a][b][m][n] = (f32x4){0.f, 0.f, 0.f, 0.f};
;         cur = nxt; cA = nA; cB = nB; ++ui;
;         if (wr == 1) PG8_BAR;
	v_rcp_f32_e32 v154, v154
	v_rcp_f32_e32 v156, v156
	v_rcp_f32_e32 v151, v151
	v_rcp_f32_e32 v153, v153
	v_rcp_f32_e32 v155, v155
	v_rcp_f32_e32 v157, v157
	v_pk_mul_f32 v[150:151], v[62:63], v[150:151]
	v_pk_mul_f32 v[152:153], v[64:65], v[152:153]
	v_pk_mul_f32 v[154:155], v[54:55], v[154:155]
	v_pk_mul_f32 v[156:157], v[56:57], v[156:157]
	v_pk_mul_f32 v[150:151], v[150:151], v[58:59]
	v_pk_mul_f32 v[152:153], v[152:153], v[60:61]
	v_pk_mul_f32 v[154:155], v[154:155], v[50:51]
	v_pk_mul_f32 v[156:157], v[156:157], v[52:53]
	v_cvt_pk_f16_f32 v58, v150, v151
	v_cvt_pk_f16_f32 v59, v152, v153
	v_cvt_pk_f16_f32 v60, v154, v155
	v_cvt_pk_f16_f32 v61, v156, v157
	s_nop 0
	global_store_dwordx4 v[240:241], v[58:61], off
	v_add_u32_e32 v242, 0x63000, v32
	v_mov_b32_e32 v243, v33
	v_lshl_add_u64 v[242:243], v[242:243], 1, s[86:87]
	v_lshl_add_u64 v[242:243], v[242:243], 0, v[232:233]
	v_pk_mul_f32 v[158:159], v[46:47], s[18:19]
	v_pk_mul_f32 v[160:161], v[48:49], s[18:19]
	v_pk_mul_f32 v[162:163], v[38:39], s[18:19]
	v_pk_mul_f32 v[164:165], v[40:41], s[18:19]
	v_exp_f32_e32 v158, v158
	v_exp_f32_e32 v160, v160
	v_exp_f32_e32 v162, v162
	v_exp_f32_e32 v164, v164
	v_exp_f32_e32 v159, v159
	v_exp_f32_e32 v161, v161
	v_exp_f32_e32 v163, v163
	v_exp_f32_e32 v165, v165
	v_pk_add_f32 v[158:159], v[158:159], 1.0 op_sel_hi:[1,0]
	v_pk_add_f32 v[160:161], v[160:161], 1.0 op_sel_hi:[1,0]
	v_pk_add_f32 v[162:163], v[162:163], 1.0 op_sel_hi:[1,0]
	v_pk_add_f32 v[164:165], v[164:165], 1.0 op_sel_hi:[1,0]
	v_rcp_f32_e32 v158, v158
	v_rcp_f32_e32 v160, v160
	v_rcp_f32_e32 v162, v162
	v_rcp_f32_e32 v164, v164
	v_rcp_f32_e32 v159, v159
	v_rcp_f32_e32 v161, v161
	v_rcp_f32_e32 v163, v163
	v_rcp_f32_e32 v165, v165
	v_pk_mul_f32 v[158:159], v[46:47], v[158:159]
	v_pk_mul_f32 v[160:161], v[48:49], v[160:161]
	v_pk_mul_f32 v[162:163], v[38:39], v[162:163]
	v_pk_mul_f32 v[164:165], v[40:41], v[164:165]
	v_pk_mul_f32 v[158:159], v[158:159], v[42:43]
	v_pk_mul_f32 v[160:161], v[160:161], v[44:45]
	v_pk_mul_f32 v[162:163], v[162:163], v[34:35]
	v_pk_mul_f32 v[164:165], v[164:165], v[36:37]
	v_cvt_pk_f16_f32 v42, v158, v159
	v_cvt_pk_f16_f32 v43, v160, v161
	v_cvt_pk_f16_f32 v44, v162, v163
	v_cvt_pk_f16_f32 v45, v164, v165
	s_nop 0
	global_store_dwordx4 v[242:243], v[42:45], off
	v_add_u32_e32 v244, 0x6e000, v32
	v_mov_b32_e32 v245, v33
	v_lshl_add_u64 v[244:245], v[244:245], 1, s[86:87]
	v_lshl_add_u64 v[244:245], v[244:245], 0, v[232:233]
	v_pk_mul_f32 v[150:151], v[28:29], s[18:19]
	v_pk_mul_f32 v[152:153], v[30:31], s[18:19]
	v_pk_mul_f32 v[154:155], v[20:21], s[18:19]
	v_pk_mul_f32 v[156:157], v[22:23], s[18:19]
	v_exp_f32_e32 v150, v150
	v_exp_f32_e32 v152, v152
	v_exp_f32_e32 v154, v154
	v_exp_f32_e32 v156, v156
	v_exp_f32_e32 v151, v151
	v_exp_f32_e32 v153, v153
	v_exp_f32_e32 v155, v155
	v_exp_f32_e32 v157, v157
	v_pk_add_f32 v[150:151], v[150:151], 1.0 op_sel_hi:[1,0]
	v_pk_add_f32 v[152:153], v[152:153], 1.0 op_sel_hi:[1,0]
	v_pk_add_f32 v[154:155], v[154:155], 1.0 op_sel_hi:[1,0]
	v_pk_add_f32 v[156:157], v[156:157], 1.0 op_sel_hi:[1,0]
	v_rcp_f32_e32 v150, v150
	v_rcp_f32_e32 v152, v152
	v_rcp_f32_e32 v154, v154
	v_rcp_f32_e32 v156, v156
	v_rcp_f32_e32 v151, v151
	v_rcp_f32_e32 v153, v153
	v_rcp_f32_e32 v155, v155
	v_rcp_f32_e32 v157, v157
	v_pk_mul_f32 v[150:151], v[28:29], v[150:151]
	v_pk_mul_f32 v[152:153], v[30:31], v[152:153]
	v_pk_mul_f32 v[154:155], v[20:21], v[154:155]
	v_pk_mul_f32 v[156:157], v[22:23], v[156:157]
	v_pk_mul_f32 v[150:151], v[150:151], v[24:25]
	v_pk_mul_f32 v[152:153], v[152:153], v[26:27]
	v_pk_mul_f32 v[154:155], v[154:155], v[16:17]
	v_pk_mul_f32 v[156:157], v[156:157], v[18:19]
	v_cvt_pk_f16_f32 v24, v150, v151
	v_cvt_pk_f16_f32 v25, v152, v153
	v_cvt_pk_f16_f32 v26, v154, v155
	v_cvt_pk_f16_f32 v27, v156, v157
	s_nop 0
	global_store_dwordx4 v[244:245], v[24:27], off
	v_add_u32_e32 v32, 0x79000, v32
	v_lshl_add_u64 v[246:247], v[32:33], 1, s[86:87]
	v_lshl_add_u64 v[246:247], v[246:247], 0, v[232:233]
	v_pk_mul_f32 v[158:159], v[12:13], s[18:19]
	v_pk_mul_f32 v[160:161], v[14:15], s[18:19]
	v_pk_mul_f32 v[162:163], v[4:5], s[18:19]
	v_pk_mul_f32 v[164:165], v[6:7], s[18:19]
	v_exp_f32_e32 v158, v158
	v_exp_f32_e32 v160, v160
	v_exp_f32_e32 v162, v162
	v_exp_f32_e32 v164, v164
	v_exp_f32_e32 v159, v159
	v_exp_f32_e32 v161, v161
	v_exp_f32_e32 v163, v163
	v_exp_f32_e32 v165, v165
	v_pk_add_f32 v[158:159], v[158:159], 1.0 op_sel_hi:[1,0]
	v_pk_add_f32 v[160:161], v[160:161], 1.0 op_sel_hi:[1,0]
	v_pk_add_f32 v[162:163], v[162:163], 1.0 op_sel_hi:[1,0]
	v_pk_add_f32 v[164:165], v[164:165], 1.0 op_sel_hi:[1,0]
	v_rcp_f32_e32 v158, v158
	v_rcp_f32_e32 v160, v160
	v_rcp_f32_e32 v162, v162
	v_rcp_f32_e32 v164, v164
	v_rcp_f32_e32 v159, v159
	v_rcp_f32_e32 v161, v161
	v_rcp_f32_e32 v163, v163
	v_rcp_f32_e32 v165, v165
	v_pk_mul_f32 v[158:159], v[12:13], v[158:159]
	v_pk_mul_f32 v[160:161], v[14:15], v[160:161]
	v_pk_mul_f32 v[162:163], v[4:5], v[162:163]
	v_pk_mul_f32 v[164:165], v[6:7], v[164:165]
	v_pk_mul_f32 v[158:159], v[158:159], v[8:9]
	v_pk_mul_f32 v[160:161], v[160:161], v[10:11]
	v_pk_mul_f32 v[162:163], v[162:163], v[0:1]
	v_pk_mul_f32 v[164:165], v[164:165], v[2:3]
	v_cvt_pk_f16_f32 v8, v158, v159
	v_cvt_pk_f16_f32 v9, v160, v161
	v_cvt_pk_f16_f32 v10, v162, v163
	v_cvt_pk_f16_f32 v11, v164, v165
	s_nop 0
	global_store_dwordx4 v[246:247], v[8:11], off
	s_cbranch_vccnz .LBB0_749
	s_andn2_b64 vcc, exec, s[0:1]
	s_cbranch_vccnz .LBB0_748
	s_nop 0
	s_branch .LBB0_748
